# odd workgroups (odd XCDs) run the small-tile tail path before the main 256x256 unit in P8/P9/P10/P11, staggering the two halves' memory-bound epilogues
# speedup vs baseline: 1.0011x; 1.0011x over previous
_Z4mega6Params:
	s_mov_b32 s100, 0
	s_mov_b32 s98, 0
	s_load_dwordx8 s[24:31], s[0:1], 0xc0
	s_add_u32 s4, s0, 0xe0
	s_addc_u32 s5, s1, 0
	s_load_dword s34, s[0:1], 0xe0
	v_writelane_b32 v238, s4, 0
	s_nop 1
	v_writelane_b32 v238, s5, 1
	s_waitcnt lgkmcnt(0)
	s_add_u32 s4, s28, 0xf18d400
	s_addc_u32 s5, s29, 0
	v_writelane_b32 v238, s4, 2
	s_sub_i32 s3, s31, s30
	s_cmp_lt_i32 s3, 2
	v_writelane_b32 v238, s5, 3
	s_mov_b32 s3, 0
	v_writelane_b32 v238, s3, 4
	s_cbranch_scc1 .LBB0_17
	v_and_b32_e32 v1, 0x3ff, v0
	v_cmp_gt_u32_e32 vcc, 2, v1
	s_and_saveexec_b64 s[4:5], vcc
	v_lshl_add_u32 v2, v1, 2, 0
	v_add_u32_e32 v2, 0x23fc0, v2
	v_mov_b32_e32 v3, 0
	ds_write_b32 v2, v3
	s_or_b64 exec, exec, s[4:5]
	s_waitcnt lgkmcnt(0)
	s_barrier
	s_getreg_b32 s3, hwreg(HW_REG_XCC_ID, 0, 4)
	s_and_b32 s3, s3, 15
	v_cmp_eq_u32_e32 vcc, 0, v1
	v_writelane_b32 v238, s3, 4
	s_and_saveexec_b64 s[4:5], vcc
	s_cbranch_execz .LBB0_6
	s_mov_b64 s[6:7], exec
	v_mbcnt_lo_u32_b32 v2, s6, 0
	v_mbcnt_hi_u32_b32 v2, s7, v2
	v_cmp_eq_u32_e32 vcc, 0, v2
	s_and_b64 s[8:9], exec, vcc
	s_mov_b64 exec, s[8:9]
	s_cbranch_execz .LBB0_6
	v_readlane_b32 s3, v238, 4
	s_bcnt1_i32_b64 s6, s[6:7]
	s_lshl_b32 s3, s3, 8
	v_mov_b32_e32 v3, s6
	v_readlane_b32 s6, v238, 2
	v_mov_b32_e32 v2, s3
	v_readlane_b32 s7, v238, 3
	s_nop 4
	global_atomic_add v2, v3, s[6:7] offset:1024

.Ltf_P8_redo:
	s_add_u32 s20, s28, 0x7e80000
	s_addc_u32 s21, s29, 0
	s_add_u32 s4, s28, 0x2300000
	s_addc_u32 s5, s29, 0
	v_and_b32_e32 v168, 0x3ff, v0
	s_cmpk_lt_i32 s2, 0x100
	s_cselect_b64 s[6:7], -1, 0
	s_cmpk_gt_i32 s2, 0xff
	v_readfirstlane_b32 s12, v168
	s_cmp_lg_u32 s100, 0
	s_cbranch_scc1 .Ltf_P8_go
	s_bitcmp1_b32 s2, 0
	s_cbranch_scc0 .Ltf_P8_go
	s_mov_b32 s100, 1
	s_branch .LBB0_2877
.Ltf_P8_go:
	s_cmpk_gt_i32 s2, 0xff
	s_cbranch_scc1 .LBB0_2877
	s_ashr_i32 s3, s2, 31
	s_lshr_b32 s0, s3, 29
	s_add_i32 s9, s2, s0
	s_and_b32 s0, s9, -8
	s_sub_i32 s10, s2, s0
	s_cmp_gt_i32 s10, -1
	s_cbranch_scc0 .LBB0_2856
	s_lshl_b32 s8, s10, 5
	s_cbranch_execz .LBB0_2857
	s_branch .LBB0_2858

.LBB0_2877:
	s_andn2_b64 vcc, exec, s[6:7]
	v_readfirstlane_b32 s0, v168
	s_cbranch_vccnz .LBB0_2898
	s_cmp_eq_u32 s100, 2
	s_cbranch_scc1 .LBB0_2898
	s_cmpk_lt_u32 s0, 0x100
	s_cselect_b64 s[8:9], -1, 0
	s_waitcnt lgkmcnt(0)
	v_lshlrev_b32_e32 v3, 3, v168
	s_lshr_b32 s1, s0, 2
	v_bfe_u32 v2, v168, 4, 2
	v_and_b32_e32 v59, 0x78, v3
	s_and_b32 s1, s1, 48
	s_lshr_b32 s3, s0, 4
	v_lshlrev_b32_e32 v38, 1, v59
	v_mov_b32_e32 v39, 0
	v_lshlrev_b32_e32 v4, 3, v2
	s_and_b32 s7, s3, 0xffffffc
	v_lshl_or_b32 v61, v2, 2, s1
	v_add_u32_e32 v2, 0x200, v168
	v_lshl_add_u64 v[42:43], s[4:5], 0, v[38:39]
	v_or_b32_e32 v3, s1, v1
	v_lshrrev_b32_e32 v62, 4, v2
	v_or_b32_e32 v2, 0x400, v168
	s_movk_i32 s4, 0x500
	s_and_b32 s3, s3, 0xffffff0
	s_add_i32 s7, s7, 32
	s_movk_i32 s6, 0x110
	v_mul_u32_u24_e32 v60, 0x110, v3
	v_lshrrev_b32_e32 v3, 4, v2
	v_cmp_gt_u32_e64 s[4:5], s4, v2
	v_or_b32_e32 v2, s3, v1
	s_and_b32 s12, s7, 0x1ffffff0
	v_mul_lo_u32 v68, v2, s6
	v_or_b32_e32 v2, s12, v1
	v_mul_lo_u32 v69, v2, s6
	v_and_b32_e32 v2, 15, v168
	v_lshl_add_u64 v[40:41], s[20:21], 0, v[38:39]
	v_lshlrev_b32_e32 v38, 4, v2
	s_movk_i32 s0, 0x300
	v_cndmask_b32_e64 v64, 0, v3, s[4:5]
	v_mul_u32_u24_e32 v67, 0x110, v3
	v_lshl_add_u64 v[2:3], s[28:29], 0, v[38:39]
	s_mov_b64 s[6:7], 0x7e80100
	v_lshrrev_b32_e32 v58, 4, v168
	v_cmp_gt_u32_e64 s[0:1], s0, v168
	v_lshl_add_u64 v[44:45], v[2:3], 0, s[6:7]
	s_mov_b64 s[6:7], 0x2300100
	v_cndmask_b32_e64 v63, 0, v62, s[0:1]
	v_mul_u32_u24_e32 v65, 0x110, v58
	v_mul_u32_u24_e32 v66, 0x110, v62
	v_mul_u32_u24_e32 v70, 0x110, v1
	v_lshl_add_u64 v[46:47], v[2:3], 0, s[6:7]
	v_lshlrev_b32_e32 v38, 1, v4
	s_mov_b32 s13, s2
	s_branch .LBB0_2880

.LBB0_2898:
	s_cmp_lg_u32 s100, 1
	s_cbranch_scc1 .Ltf_P8_end
	s_mov_b32 s100, 2
	s_branch .Ltf_P8_redo
.Ltf_P8_end:
	s_mov_b32 s100, 0
	s_cmp_lt_i32 s30, 10
	s_cselect_b64 s[12:13], -1, 0
	s_cmp_gt_i32 s30, 9
	s_cselect_b64 s[0:1], -1, 0
	s_cmp_lt_i32 s31, 10
	s_cselect_b64 s[4:5], -1, 0
	s_or_b64 s[0:1], s[0:1], s[4:5]
	s_and_b64 vcc, exec, s[0:1]
	s_cbranch_vccnz .LBB0_2957
.Ltf_P9_redo:
	s_add_u32 s6, s28, 0x1f00000
	v_and_b32_e32 v161, 0x3ff, v0
	s_addc_u32 s7, s29, 0
	v_bfe_u32 v162, v161, 4, 2
	v_readfirstlane_b32 s16, v161
	s_cmpk_gt_i32 s2, 0x1ff
	v_lshlrev_b32_e32 v160, 3, v162
	s_cmp_lg_u32 s100, 0
	s_cbranch_scc1 .Ltf_P9_go
	s_bitcmp1_b32 s2, 0
	s_cbranch_scc0 .Ltf_P9_go
	s_mov_b32 s100, 1
	s_branch .LBB0_2923
.Ltf_P9_go:
	s_cmpk_gt_i32 s2, 0x1ff
	s_cbranch_scc1 .LBB0_2923
	s_ashr_i32 s3, s2, 31
	s_lshr_b32 s0, s3, 29
	s_add_i32 s5, s2, s0
	s_and_b32 s0, s5, -8
	s_sub_i32 s8, s2, s0
	s_cmp_gt_i32 s8, -1
	s_cbranch_scc0 .LBB0_2902
	s_lshl_b32 s4, s8, 6
	s_cbranch_execz .LBB0_2903
	s_branch .LBB0_2904

.LBB0_2923:
	s_lshl_b32 s3, s2, 1
	s_cmpk_gt_i32 s3, 0x1ff
	v_readfirstlane_b32 s0, v161
	s_cbranch_scc1 .LBB0_2957
	s_cmp_eq_u32 s100, 2
	s_cbranch_scc1 .LBB0_2957
	s_cmpk_lt_u32 s0, 0x100
	v_lshlrev_b32_e32 v2, 3, v161
	s_cselect_b64 s[16:17], -1, 0
	v_and_b32_e32 v59, 0x78, v2
	s_lshr_b32 s1, s0, 2
	v_lshlrev_b32_e32 v2, 1, v59
	s_waitcnt lgkmcnt(0)
	v_mov_b32_e32 v3, 0
	s_and_b32 s1, s1, 48
	v_lshl_add_u64 v[38:39], s[88:89], 0, v[2:3]
	v_lshl_add_u64 v[40:41], s[6:7], 0, v[2:3]
	v_or_b32_e32 v2, s1, v1
	v_mul_u32_u24_e32 v60, 0x110, v2
	s_lshr_b32 s7, s0, 4
	v_lshlrev_b32_e32 v2, 4, v162
	s_and_b32 s8, s7, 0xffffffc
	v_lshl_add_u64 v[42:43], s[76:77], 0, v[2:3]
	v_add_u32_e32 v2, 0x200, v161
	v_lshrrev_b32_e32 v62, 4, v2
	v_or_b32_e32 v2, 0x400, v161
	s_movk_i32 s4, 0x500
	s_and_b32 s33, s7, 0xffffff0
	s_add_i32 s8, s8, 32
	s_movk_i32 s6, 0x110
	v_lshrrev_b32_e32 v4, 4, v2
	v_cmp_gt_u32_e64 s[4:5], s4, v2
	v_or_b32_e32 v2, s33, v1
	s_and_b32 s35, s8, 0x1ffffff0
	v_mul_lo_u32 v68, v2, s6
	v_or_b32_e32 v2, s35, v1
	v_mul_lo_u32 v69, v2, s6
	v_and_b32_e32 v2, 15, v161
	v_lshlrev_b32_e32 v2, 4, v2
	v_lshl_add_u64 v[2:3], s[28:29], 0, v[2:3]
	s_mov_b64 s[6:7], 0x3980100
	s_movk_i32 s0, 0x300
	s_lshl_b32 s40, s34, 1
	v_lshl_add_u64 v[44:45], v[2:3], 0, s[6:7]
	s_mov_b64 s[6:7], 0x1f00100
	v_bfe_u32 v58, v0, 4, 6
	v_lshl_or_b32 v61, v162, 2, s1
	v_cmp_gt_u32_e64 s[0:1], s0, v161
	s_add_u32 s18, s28, 0xf191400
	v_lshl_add_u64 v[46:47], v[2:3], 0, s[6:7]
	v_mbcnt_lo_u32_b32 v2, -1, 0
	v_cndmask_b32_e64 v63, 0, v62, s[0:1]
	v_cndmask_b32_e64 v64, 0, v4, s[4:5]
	v_mul_u32_u24_e32 v65, 0x110, v58
	v_mul_u32_u24_e32 v66, 0x110, v62
	v_mul_u32_u24_e32 v67, 0x110, v4
	v_mul_u32_u24_e32 v70, 0x110, v1
	s_addc_u32 s19, s29, 0
	v_mov_b32_e32 v71, 0x358637bd
	s_mov_b32 s41, 0x800000
	v_mbcnt_hi_u32_b32 v72, -1, v2
	v_mov_b32_e32 v73, 0x7c
	s_branch .LBB0_2926

.Ltf_P9_end:
	s_mov_b32 s100, 0
	s_cmp_gt_i32 s31, 10
	s_cselect_b64 s[0:1], -1, 0
	s_and_b64 s[4:5], s[12:13], s[0:1]
	s_andn2_b64 vcc, exec, s[4:5]
	s_cbranch_vccnz .LBB0_3011
	s_waitcnt vmcnt(0)
	v_and_b32_e32 v2, 0x3ff, v0
	v_cmp_eq_u32_e32 vcc, 0, v2
	s_waitcnt vmcnt(0) lgkmcnt(0)
	s_barrier
	s_and_saveexec_b64 s[4:5], vcc
	s_cbranch_execz .LBB0_3010
	s_add_i32 s3, 0, 0x23fc0
	v_mov_b32_e32 v2, s3
	s_waitcnt vmcnt(0) expcnt(0) lgkmcnt(0)
	ds_read_b32 v4, v2
	s_add_i32 s3, 0, 0x23fc4
	v_mov_b32_e32 v2, s3
	ds_read_b32 v2, v2
	s_waitcnt lgkmcnt(1)
	v_cmp_ne_u32_e32 vcc, 0, v4
	s_cbranch_vccnz .LBB0_2974
	v_readlane_b32 s6, v238, 0
	v_readlane_b32 s7, v238, 1
	s_load_dwordx2 s[10:11], s[6:7], 0x4
	s_add_u32 s6, s28, 0xf18d600
	s_addc_u32 s7, s29, 0
	s_add_u32 s8, s28, 0xf18d800
	s_addc_u32 s9, s29, 0
	s_waitcnt lgkmcnt(0)
	s_mul_i32 s3, s10, s34
	s_add_u32 s10, s28, 0xf18d900
	s_mul_i32 s3, s3, s11
	s_addc_u32 s11, s29, 0
	s_add_u32 s12, s28, 0xf18da00
	s_addc_u32 s13, s29, 0
	s_add_u32 s16, s28, 0xf18db00
	s_addc_u32 s17, s29, 0
	s_add_u32 s18, s28, 0xf18dc00
	s_addc_u32 s19, s29, 0
	s_add_u32 s20, s28, 0xf18dd00
	s_addc_u32 s21, s29, 0
	s_add_u32 s22, s28, 0xf18de00
	s_addc_u32 s23, s29, 0
	s_add_u32 s36, s28, 0xf18df00
	s_addc_u32 s37, s29, 0
	s_add_u32 s38, s28, 0xf18e000
	s_addc_u32 s39, s29, 0
	s_add_u32 s40, s28, 0xf18e100
	s_addc_u32 s41, s29, 0
	s_add_u32 s42, s28, 0xf18e200
	s_addc_u32 s43, s29, 0
	s_add_u32 s44, s28, 0xf18e300
	s_addc_u32 s45, s29, 0
	s_add_u32 s46, s28, 0xf18e400
	s_addc_u32 s47, s29, 0
	s_add_u32 s48, s28, 0xf18e500
	s_addc_u32 s49, s29, 0
	s_add_u32 s50, s28, 0xf18e600
	s_addc_u32 s51, s29, 0
	s_add_u32 s52, s28, 0xf18e700
	s_addc_u32 s53, s29, 0
	s_mov_b32 s33, 1
	v_mov_b32_e32 v18, 0
	s_branch .LBB0_2962

.Ltf_P10_redo:
	s_add_u32 s14, s28, 0xa100000
	s_addc_u32 s15, s29, 0
	s_add_u32 s4, s28, 0x2500000
	s_addc_u32 s5, s29, 0
	v_and_b32_e32 v164, 0x3ff, v0
	s_cmpk_lt_i32 s2, 0x100
	s_cselect_b64 s[6:7], -1, 0
	s_cmpk_gt_i32 s2, 0xff
	v_readfirstlane_b32 s16, v164
	s_cmp_lg_u32 s100, 0
	s_cbranch_scc1 .Ltf_P10_go
	s_bitcmp1_b32 s2, 0
	s_cbranch_scc0 .Ltf_P10_go
	s_mov_b32 s100, 1
	s_branch .LBB0_3036
.Ltf_P10_go:
	s_cmpk_gt_i32 s2, 0xff
	s_cbranch_scc1 .LBB0_3036
	s_ashr_i32 s3, s2, 31
	s_lshr_b32 s0, s3, 29
	s_add_i32 s11, s2, s0
	s_and_b32 s0, s11, -8
	s_sub_i32 s12, s2, s0
	s_cmp_gt_i32 s12, -1
	s_cbranch_scc0 .LBB0_3015
	s_lshl_b32 s10, s12, 5
	s_cbranch_execz .LBB0_3016
	s_branch .LBB0_3017

.LBB0_3036:
	s_andn2_b64 vcc, exec, s[6:7]
	v_readfirstlane_b32 s0, v164
	s_cbranch_vccnz .LBB0_3057
	s_cmp_eq_u32 s100, 2
	s_cbranch_scc1 .LBB0_3057
	s_cmpk_lt_u32 s0, 0x100
	s_cselect_b64 s[10:11], -1, 0
	s_waitcnt lgkmcnt(0)
	v_lshlrev_b32_e32 v3, 3, v164
	s_lshr_b32 s1, s0, 2
	v_bfe_u32 v2, v164, 4, 2
	v_and_b32_e32 v59, 0x78, v3
	s_and_b32 s1, s1, 48
	s_lshr_b32 s3, s0, 4
	v_lshlrev_b32_e32 v38, 1, v59
	v_mov_b32_e32 v39, 0
	v_lshlrev_b32_e32 v4, 3, v2
	s_and_b32 s7, s3, 0xffffffc
	v_lshl_or_b32 v61, v2, 2, s1
	v_add_u32_e32 v2, 0x200, v164
	v_lshl_add_u64 v[42:43], s[4:5], 0, v[38:39]
	v_or_b32_e32 v3, s1, v1
	v_lshrrev_b32_e32 v62, 4, v2
	v_or_b32_e32 v2, 0x400, v164
	s_movk_i32 s4, 0x500
	s_and_b32 s3, s3, 0xffffff0
	s_add_i32 s7, s7, 32
	v_lshl_add_u64 v[40:41], s[14:15], 0, v[38:39]
	s_movk_i32 s6, 0x110
	v_mul_u32_u24_e32 v60, 0x110, v3
	v_lshrrev_b32_e32 v3, 4, v2
	v_cmp_gt_u32_e64 s[4:5], s4, v2
	v_or_b32_e32 v2, s3, v1
	s_and_b32 s14, s7, 0x1ffffff0
	v_mul_lo_u32 v68, v2, s6
	v_or_b32_e32 v2, s14, v1
	v_mul_lo_u32 v69, v2, s6
	v_and_b32_e32 v2, 15, v164
	v_lshlrev_b32_e32 v38, 4, v2
	s_movk_i32 s0, 0x300
	v_cndmask_b32_e64 v64, 0, v3, s[4:5]
	v_mul_u32_u24_e32 v67, 0x110, v3
	v_lshl_add_u64 v[2:3], s[28:29], 0, v[38:39]
	s_mov_b64 s[6:7], 0xa100100
	v_lshrrev_b32_e32 v58, 4, v164
	v_cmp_gt_u32_e64 s[0:1], s0, v164
	v_lshl_add_u64 v[44:45], v[2:3], 0, s[6:7]
	s_mov_b64 s[6:7], 0x2500100
	v_cndmask_b32_e64 v63, 0, v62, s[0:1]
	v_mul_u32_u24_e32 v65, 0x110, v58
	v_mul_u32_u24_e32 v66, 0x110, v62
	v_mul_u32_u24_e32 v70, 0x110, v1
	v_lshl_add_u64 v[46:47], v[2:3], 0, s[6:7]
	v_lshlrev_b32_e32 v38, 1, v4
	s_mov_b32 s15, s2
	s_branch .LBB0_3039

.Ltf_P10_end:
	s_mov_b32 s100, 0
	s_cmp_gt_i32 s31, 11
	s_cselect_b64 s[0:1], -1, 0
	s_and_b64 s[4:5], s[8:9], s[0:1]
	s_andn2_b64 vcc, exec, s[4:5]
	s_cbranch_vccnz .LBB0_3111
	s_waitcnt vmcnt(0)
	v_and_b32_e32 v1, 0x3ff, v0
	v_cmp_eq_u32_e32 vcc, 0, v1
	s_waitcnt vmcnt(0) lgkmcnt(0)
	s_barrier
	s_and_saveexec_b64 s[4:5], vcc
	s_cbranch_execz .LBB0_3110
	s_add_i32 s3, 0, 0x23fc0
	v_mov_b32_e32 v1, s3
	s_waitcnt vmcnt(0) expcnt(0) lgkmcnt(0)
	ds_read_b32 v3, v1
	s_add_i32 s3, 0, 0x23fc4
	v_mov_b32_e32 v1, s3
	ds_read_b32 v1, v1
	s_waitcnt lgkmcnt(1)
	v_cmp_ne_u32_e32 vcc, 0, v3
	s_cbranch_vccnz .LBB0_3074
	v_readlane_b32 s6, v238, 0
	v_readlane_b32 s7, v238, 1
	s_load_dwordx2 s[10:11], s[6:7], 0x4
	s_add_u32 s6, s28, 0xf18d600
	s_addc_u32 s7, s29, 0
	s_add_u32 s8, s28, 0xf18d800
	s_addc_u32 s9, s29, 0
	s_waitcnt lgkmcnt(0)
	s_mul_i32 s3, s10, s34
	s_add_u32 s10, s28, 0xf18d900
	s_mul_i32 s3, s3, s11
	s_addc_u32 s11, s29, 0
	s_add_u32 s12, s28, 0xf18da00
	s_addc_u32 s13, s29, 0
	s_add_u32 s14, s28, 0xf18db00
	s_addc_u32 s15, s29, 0
	s_add_u32 s16, s28, 0xf18dc00
	s_addc_u32 s17, s29, 0
	s_add_u32 s18, s28, 0xf18dd00
	s_addc_u32 s19, s29, 0
	s_add_u32 s20, s28, 0xf18de00
	s_addc_u32 s21, s29, 0
	s_add_u32 s22, s28, 0xf18df00
	s_addc_u32 s23, s29, 0
	s_add_u32 s36, s28, 0xf18e000
	s_addc_u32 s37, s29, 0
	s_add_u32 s38, s28, 0xf18e100
	s_addc_u32 s39, s29, 0
	s_add_u32 s40, s28, 0xf18e200
	s_addc_u32 s41, s29, 0
	s_add_u32 s42, s28, 0xf18e300
	s_addc_u32 s43, s29, 0
	s_add_u32 s44, s28, 0xf18e400
	s_addc_u32 s45, s29, 0
	s_add_u32 s46, s28, 0xf18e500
	s_addc_u32 s47, s29, 0
	s_add_u32 s48, s28, 0xf18e600
	s_addc_u32 s49, s29, 0
	s_add_u32 s50, s28, 0xf18e700
	s_addc_u32 s51, s29, 0
	s_mov_b32 s33, 1
	v_mov_b32_e32 v17, 0
	s_branch .LBB0_3062

.Ltf_P11_redo:
	v_and_b32_e32 v1, 0x3ff, v0
	s_cmpk_lt_i32 s2, 0x100
	s_cselect_b64 s[4:5], -1, 0
	s_cmpk_gt_i32 s2, 0xff
	v_readfirstlane_b32 s6, v1
	s_cbranch_scc1 .LBB0_3118
	s_ashr_i32 s0, s2, 31
	s_lshr_b32 s0, s0, 29
	s_add_i32 s3, s2, s0
	s_and_b32 s0, s3, -8
	s_sub_i32 s7, s2, s0
	s_cmp_gt_i32 s7, -1
	s_cbranch_scc0 .LBB0_3115
	s_lshl_b32 s8, s7, 5
	s_cbranch_execz .LBB0_3116
	s_branch .LBB0_3117

.LBB0_3118:
	s_add_u32 s8, s28, 0x2700000
	v_bfe_u32 v165, v1, 4, 2
	v_cndmask_b32_e64 v2, 0, 1, s[4:5]
	s_addc_u32 s9, s29, 0
	v_lshlrev_b32_e32 v162, 4, v1
	v_and_b32_e32 v164, 15, v1
	v_cmp_ne_u32_e64 s[0:1], 1, v2
	s_andn2_b64 vcc, exec, s[4:5]
	v_lshlrev_b32_e32 v163, 3, v165
	s_cmp_lg_u32 s100, 0
	s_cbranch_scc1 .Ltf_P11_go
	s_bitcmp1_b32 s2, 0
	s_cbranch_scc0 .Ltf_P11_go
	s_mov_b32 s100, 1
	s_branch .LBB0_3186
.Ltf_P11_go:
	s_cbranch_vccnz .LBB0_3186
	s_waitcnt lgkmcnt(0)
	v_lshrrev_b32_e32 v3, 1, v1
	v_lshrrev_b32_e32 v4, 5, v1
	v_and_b32_e32 v3, 24, v3
	v_and_b32_e32 v4, 4, v4
	v_bfe_u32 v5, v1, 2, 2
	v_and_b32_e32 v2, 32, v1
	v_bfe_u32 v12, v1, 2, 4
	v_or3_b32 v3, v4, v5, v3
	v_lshrrev_b32_e32 v4, 3, v1
	s_movk_i32 s3, 0x70
	v_bitop3_b32 v10, v162, v2, 48 bitop3:0x6c
	v_and_b32_e32 v11, 64, v1
	v_and_or_b32 v5, v4, s3, v12
	s_movk_i32 s3, 0x60
	v_or_b32_e32 v2, v10, v11
	v_and_or_b32 v4, v4, s3, v3
	v_add_u32_e32 v13, 0x2000, v162
	v_lshl_or_b32 v142, v4, 11, v2
	v_lshrrev_b32_e32 v4, 7, v13
	s_movk_i32 s3, 0xf0
	s_lshr_b32 s4, s6, 6
	v_lshl_or_b32 v140, v5, 11, v2
	v_and_or_b32 v5, v4, s3, v12
	s_movk_i32 s3, 0xe0
	s_ashr_i32 s43, s42, 31
	s_ashr_i32 s11, s10, 31
	v_and_or_b32 v3, v4, s3, v3
	s_lshr_b32 s5, s6, 8
	s_lshl_b32 s3, s4, 10
	s_lshl_b64 s[16:17], s[42:43], 19
	s_lshl_b64 s[18:19], s[10:11], 19
	s_add_u32 s46, s8, s18
	s_addc_u32 s47, s9, s19
	s_add_i32 s33, s3, 0
	s_add_i32 m0, s33, 0x10000
	v_lshl_or_b32 v146, v3, 11, v2
	global_load_lds_dwordx4 v142, s[46:47]
	s_add_i32 m0, s33, 0x12000
	s_add_u32 s18, s46, 0x40000
	global_load_lds_dwordx4 v146, s[46:47]
	s_addc_u32 s19, s47, 0
	s_add_i32 m0, s33, 0x14000
	v_lshl_or_b32 v144, v5, 11, v2
	global_load_lds_dwordx4 v142, s[18:19]
	s_add_i32 m0, s33, 0x16000
	s_add_u32 s44, s62, s16
	s_addc_u32 s45, s63, s17
	s_add_i32 s35, s33, 0x2000
	global_load_lds_dwordx4 v146, s[18:19]
	s_mov_b32 m0, s33
	s_add_u32 s16, s44, 0x40000
	global_load_lds_dwordx4 v140, s[44:45]
	s_mov_b32 m0, s35
	s_addc_u32 s17, s45, 0
	s_add_i32 s50, s33, 0x4000
	global_load_lds_dwordx4 v144, s[44:45]
	s_mov_b32 m0, s50
	s_add_i32 s51, s33, 0x6000
	global_load_lds_dwordx4 v140, s[16:17]
	s_mov_b32 m0, s51
	v_mov_b32_e32 v143, 0
	global_load_lds_dwordx4 v144, s[16:17]
	v_mov_b32_e32 v147, v143
	v_mov_b32_e32 v141, v143
	v_mov_b32_e32 v145, v143
	s_cmp_eq_u32 s5, 1
	s_mov_b32 s11, 0
	v_lshl_add_u64 v[8:9], s[46:47], 0, v[142:143]
	v_lshl_add_u64 v[6:7], s[46:47], 0, v[146:147]
	v_lshl_add_u64 v[2:3], s[44:45], 0, v[140:141]
	s_cselect_b64 s[16:17], -1, 0
	s_cmp_lg_u32 s5, 1
	v_lshl_add_u64 v[4:5], s[44:45], 0, v[144:145]
	s_cbranch_scc1 .LBB0_3121
	s_barrier

.LBB0_3186:
	s_and_b64 vcc, exec, s[0:1]
	v_readfirstlane_b32 s0, v1
	s_cbranch_vccnz .LBB0_3221
	s_cmp_eq_u32 s100, 2
	s_cbranch_scc1 .LBB0_3221
	s_cmpk_lt_u32 s0, 0x100
	s_cselect_b64 s[16:17], -1, 0
	v_lshlrev_b32_e32 v2, 3, v1
	s_lshr_b32 s3, s0, 2
	v_and_b32_e32 v59, 0x78, v2
	v_and_or_b32 v2, s3, 48, v164
	s_lshr_b32 s1, s0, 6
	v_mul_u32_u24_e32 v60, 0x110, v2
	s_bfe_u32 s4, s0, 0x20006
	v_lshlrev_b32_e32 v2, 2, v165
	v_lshlrev_b32_e32 v38, 1, v59
	v_mov_b32_e32 v39, 0
	s_lshl_b32 s10, s1, 2
	v_lshl_or_b32 v61, s4, 4, v2
	v_add_u32_e32 v2, 0x200, v1
	v_lshl_add_u64 v[42:43], s[8:9], 0, v[38:39]
	v_lshrrev_b32_e32 v62, 4, v2
	v_or_b32_e32 v2, 0x400, v1
	s_movk_i32 s8, 0x500
	s_and_b32 s11, s10, 0xffffff0
	s_add_i32 s10, s10, 32
	s_waitcnt lgkmcnt(0)
	v_lshl_add_u64 v[40:41], s[62:63], 0, v[38:39]
	s_lshl_b32 s4, s4, 2
	v_lshrrev_b32_e32 v3, 4, v2
	v_cmp_gt_u32_e64 s[8:9], s8, v2
	s_and_b32 s10, s10, 0x1ffffff0
	v_lshlrev_b32_e32 v38, 4, v164
	s_add_i32 s4, s4, 0
	v_cndmask_b32_e64 v64, 0, v3, s[8:9]
	v_mul_u32_u24_e32 v67, 0x110, v3
	v_or_b32_e32 v68, s11, v164
	v_or_b32_e32 v70, s10, v164
	v_lshl_add_u64 v[2:3], s[28:29], 0, v[38:39]
	s_mov_b64 s[10:11], 0xc380100
	s_movk_i32 s3, 0x110
	s_add_i32 s18, s4, 0x13200
	s_movk_i32 s6, 0x300
	v_lshl_add_u64 v[44:45], v[2:3], 0, s[10:11]
	s_mov_b64 s[10:11], 0x2700100
	v_lshrrev_b32_e32 v58, 4, v1
	s_movk_i32 s4, 0x50
	v_cmp_gt_u32_e64 s[6:7], s6, v1
	v_mul_lo_u32 v69, v68, s3
	v_mul_lo_u32 v71, v70, s3
	v_lshlrev_b32_e32 v4, 4, v68
	v_lshlrev_b32_e32 v5, 4, v70
	s_add_u32 s3, s28, 0xea61400
	v_lshl_add_u64 v[46:47], v[2:3], 0, s[10:11]
	v_mbcnt_lo_u32_b32 v2, -1, 0
	v_cmp_eq_u32_e64 s[0:1], 0, v165
	v_cmp_gt_u32_e64 s[4:5], s4, v1
	v_cndmask_b32_e64 v63, 0, v62, s[6:7]
	v_mul_u32_u24_e32 v65, 0x110, v58
	v_mul_u32_u24_e32 v66, 0x110, v62
	v_mul_u32_u24_e32 v72, 0x110, v164
	v_or_b32_e32 v73, 0x4040, v164
	s_addc_u32 s22, s29, 0
	s_movk_i32 s23, 0x4400
	v_add_u32_e32 v74, s18, v4
	v_add_u32_e32 v75, s18, v5
	v_add_u32_e32 v38, s18, v38
	v_mbcnt_hi_u32_b32 v76, -1, v2
	s_mov_b32 s33, s2
	s_branch .LBB0_3189

.Ltf_P11_end:
	s_mov_b32 s100, 0
	s_cmp_gt_i32 s31, 12
	s_cselect_b64 s[0:1], -1, 0
	s_and_b64 s[4:5], s[14:15], s[0:1]
	s_andn2_b64 vcc, exec, s[4:5]
	s_cbranch_vccnz .LBB0_3275
	s_waitcnt vmcnt(0)
	v_and_b32_e32 v1, 0x3ff, v0
	v_cmp_eq_u32_e32 vcc, 0, v1
	s_waitcnt vmcnt(0) lgkmcnt(0)
	s_barrier
	s_and_saveexec_b64 s[4:5], vcc
	s_cbranch_execz .LBB0_3274
	s_add_i32 s3, 0, 0x23fc0
	v_mov_b32_e32 v1, s3
	s_waitcnt vmcnt(0) expcnt(0) lgkmcnt(0)
	ds_read_b32 v3, v1
	s_add_i32 s3, 0, 0x23fc4
	v_mov_b32_e32 v1, s3
	ds_read_b32 v1, v1
	s_waitcnt lgkmcnt(1)
	v_cmp_ne_u32_e32 vcc, 0, v3
	s_cbranch_vccnz .LBB0_3238
	v_readlane_b32 s6, v238, 0
	v_readlane_b32 s7, v238, 1
	s_load_dwordx2 s[10:11], s[6:7], 0x4
	s_add_u32 s6, s28, 0xf18d600
	s_addc_u32 s7, s29, 0
	s_add_u32 s8, s28, 0xf18d800
	s_addc_u32 s9, s29, 0
	s_waitcnt lgkmcnt(0)
	s_mul_i32 s3, s10, s34
	s_add_u32 s10, s28, 0xf18d900
	s_mul_i32 s3, s3, s11
	s_addc_u32 s11, s29, 0
	s_add_u32 s14, s28, 0xf18da00
	s_addc_u32 s15, s29, 0
	s_add_u32 s16, s28, 0xf18db00
	s_addc_u32 s17, s29, 0
	s_add_u32 s18, s28, 0xf18dc00
	s_addc_u32 s19, s29, 0
	s_add_u32 s20, s28, 0xf18dd00
	s_addc_u32 s21, s29, 0
	s_add_u32 s22, s28, 0xf18de00
	s_addc_u32 s23, s29, 0
	s_add_u32 s36, s28, 0xf18df00
	s_addc_u32 s37, s29, 0
	s_add_u32 s38, s28, 0xf18e000
	s_addc_u32 s39, s29, 0
	s_add_u32 s40, s28, 0xf18e100
	s_addc_u32 s41, s29, 0
	s_add_u32 s42, s28, 0xf18e200
	s_addc_u32 s43, s29, 0
	s_add_u32 s44, s28, 0xf18e300
	s_addc_u32 s45, s29, 0
	s_add_u32 s46, s28, 0xf18e400
	s_addc_u32 s47, s29, 0
	s_add_u32 s48, s28, 0xf18e500
	s_addc_u32 s49, s29, 0
	s_add_u32 s50, s28, 0xf18e600
	s_addc_u32 s51, s29, 0
	s_add_u32 s52, s28, 0xf18e700
	s_addc_u32 s53, s29, 0
	s_mov_b32 s33, 1
	v_mov_b32_e32 v17, 0
	s_branch .LBB0_3226

	.amdhsa_kernel _Z4mega6Params
		.amdhsa_group_segment_fixed_size 0
		.amdhsa_private_segment_fixed_size 0
		.amdhsa_kernarg_size 480
		.amdhsa_user_sgpr_count 2
		.amdhsa_user_sgpr_dispatch_ptr 0
		.amdhsa_user_sgpr_queue_ptr 0
		.amdhsa_user_sgpr_kernarg_segment_ptr 1
		.amdhsa_user_sgpr_dispatch_id 0
		.amdhsa_user_sgpr_kernarg_preload_length 0
		.amdhsa_user_sgpr_kernarg_preload_offset 0
		.amdhsa_user_sgpr_private_segment_size 0
		.amdhsa_uses_dynamic_stack 0
		.amdhsa_enable_private_segment 0
		.amdhsa_system_sgpr_workgroup_id_x 1
		.amdhsa_system_sgpr_workgroup_id_y 0
		.amdhsa_system_sgpr_workgroup_id_z 0
		.amdhsa_system_sgpr_workgroup_info 0
		.amdhsa_system_vgpr_workitem_id 2
		.amdhsa_next_free_vgpr 239
		.amdhsa_next_free_sgpr 102
		.amdhsa_accum_offset 240
		.amdhsa_reserve_vcc 1
		.amdhsa_float_round_mode_32 0
		.amdhsa_float_round_mode_16_64 0
		.amdhsa_float_denorm_mode_32 3
		.amdhsa_float_denorm_mode_16_64 3
		.amdhsa_dx10_clamp 1
		.amdhsa_ieee_mode 1
		.amdhsa_fp16_overflow 0
		.amdhsa_tg_split 0
		.amdhsa_exception_fp_ieee_invalid_op 0
		.amdhsa_exception_fp_denorm_src 0
		.amdhsa_exception_fp_ieee_div_zero 0
		.amdhsa_exception_fp_ieee_overflow 0
		.amdhsa_exception_fp_ieee_underflow 0
		.amdhsa_exception_fp_ieee_inexact 0
		.amdhsa_exception_int_div_zero 0
	.end_amdhsa_kernel

amdhsa.kernels:
  - .agpr_count:     0
    .args:
      - .offset:         0
        .size:           224
        .value_kind:     by_value
      - .offset:         224
        .size:           4
        .value_kind:     hidden_block_count_x
      - .offset:         228
        .size:           4
        .value_kind:     hidden_block_count_y
      - .offset:         232
        .size:           4
        .value_kind:     hidden_block_count_z
      - .offset:         236
        .size:           2
        .value_kind:     hidden_group_size_x
      - .offset:         238
        .size:           2
        .value_kind:     hidden_group_size_y
      - .offset:         240
        .size:           2
        .value_kind:     hidden_group_size_z
      - .offset:         242
        .size:           2
        .value_kind:     hidden_remainder_x
      - .offset:         244
        .size:           2
        .value_kind:     hidden_remainder_y
      - .offset:         246
        .size:           2
        .value_kind:     hidden_remainder_z
      - .offset:         264
        .size:           8
        .value_kind:     hidden_global_offset_x
      - .offset:         272
        .size:           8
        .value_kind:     hidden_global_offset_y
      - .offset:         280
        .size:           8
        .value_kind:     hidden_global_offset_z
      - .offset:         288
        .size:           2
        .value_kind:     hidden_grid_dims
      - .offset:         312
        .size:           8
        .value_kind:     hidden_multigrid_sync_arg
      - .offset:         344
        .size:           4
        .value_kind:     hidden_dynamic_lds_size
    .group_segment_fixed_size: 0
    .kernarg_segment_align: 8
    .kernarg_segment_size: 480
    .language:       OpenCL C
    .language_version:
      - 2
      - 0
    .max_flat_workgroup_size: 512
    .name:           _Z4mega6Params
    .private_segment_fixed_size: 0
    .sgpr_count:     108
    .sgpr_spill_count: 56
    .symbol:         _Z4mega6Params.kd
    .uniform_work_group_size: 1
    .uses_dynamic_stack: false
    .vgpr_count:     239
    .vgpr_spill_count: 0
    .wavefront_size: 64
